# x1-skip plus P4 row loop: c_kv/krope/rope-table loads hoisted next to the c_q load (one latency per row)
# speedup vs baseline: 1.0059x; 1.0016x over previous
; __global__ void __launch_bounds__(512, 2) fwd_kernel(Args a) {
;     ...
;             { const u32x4 v = *(const u32x4*)(pr + PC_CQ + lane * 8); float s = 0.f;
;               s += bflo(v.x) * bflo(v.x) + bfhi(v.x) * bfhi(v.x) + bflo(v.y) * bflo(v.y) + bfhi(v.y) * bfhi(v.y) + bflo(v.z) * bflo(v.z) + bfhi(v.z) * bfhi(v.z) + bflo(v.w) * bflo(v.w) + bfhi(v.w) * bfhi(v.w);
;               s = wave_sum(s); if (lane == 0) rstd_q[m] = 1.0f / sqrtf(s * (1.0f / 512.0f) + RMS_EPS); }
;             { float s = 0.f; if (lane < 32) { const u32x4 v = *(const u32x4*)(pr + PC_CKV + lane * 8);
;               s += bflo(v.x) * bflo(v.x) + bfhi(v.x) * bfhi(v.x) + bflo(v.y) * bflo(v.y) + bfhi(v.y) * bfhi(v.y) + bflo(v.z) * bflo(v.z) + bfhi(v.z) * bfhi(v.z) + bflo(v.w) * bflo(v.w) + bfhi(v.w) * bfhi(v.w); }
;               s = wave_sum(s); if (lane == 0) rstd_kv[m] = 1.0f / sqrtf(s * (1.0f / 256.0f) + RMS_EPS); }
;             if (lane < 8) { const u32x4 v = *(const u32x4*)(pr + PC_KR + lane * 8); const int pos = m & (SEQ - 1), i0 = lane * 4;
.LBB0_489:
	v_lshl_add_u64 v[10:11], s[18:19], 0, v[8:9]
	v_add_co_u32_e32 v56, vcc, 0x7c01000, v10
	s_waitcnt lgkmcnt(0)
	s_nop 0
	v_addc_co_u32_e32 v57, vcc, 0, v11, vcc
	global_load_dwordx4 v[22:25], v[56:57], off offset:2048
	s_and_saveexec_b64 s[24:25], s[4:5]
	global_load_dwordx4 v[40:43], v[56:57], off offset:3072
	s_or_b64 exec, exec, s[24:25]
	s_and_b32 s8, s15, 0x1ffe0
	s_lshl_b32 s8, s8, 2
	s_and_saveexec_b64 s[24:25], s[6:7]
	global_load_dwordx4 v[44:47], v[56:57], off offset:3712
	v_lshl_add_u64 v[58:59], v[4:5], 0, s[8:9]
	global_load_dwordx4 v[48:51], v[58:59], off
	v_lshl_add_u64 v[58:59], v[2:3], 0, s[8:9]
	global_load_dwordx4 v[52:55], v[58:59], off
	s_or_b64 exec, exec, s[24:25]
	s_waitcnt vmcnt(4)
	v_lshlrev_b32_e32 v26, 16, v22
	v_and_b32_e32 v22, 0xffff0000, v22
	v_mul_f32_e32 v22, v22, v22
	v_lshlrev_b32_e32 v27, 16, v23
	v_fmac_f32_e32 v22, v26, v26
	v_and_b32_e32 v23, 0xffff0000, v23
	v_fmac_f32_e32 v22, v27, v27
	v_lshlrev_b32_e32 v28, 16, v24
	v_fmac_f32_e32 v22, v23, v23
	v_and_b32_e32 v24, 0xffff0000, v24
	v_fmac_f32_e32 v22, v28, v28
	v_lshlrev_b32_e32 v29, 16, v25
	v_fmac_f32_e32 v22, v24, v24
	v_fmac_f32_e32 v22, v29, v29
	v_and_b32_e32 v23, 0xffff0000, v25
	v_fmac_f32_e32 v22, v23, v23
	ds_bpermute_b32 v23, v12, v22
	s_waitcnt lgkmcnt(0)
	v_add_f32_e32 v22, v22, v23
	ds_bpermute_b32 v23, v13, v22
	s_waitcnt lgkmcnt(0)
	v_add_f32_e32 v22, v22, v23
	ds_bpermute_b32 v23, v14, v22
	s_waitcnt lgkmcnt(0)
	v_add_f32_e32 v22, v22, v23
	ds_bpermute_b32 v23, v15, v22
	s_waitcnt lgkmcnt(0)
	v_add_f32_e32 v22, v22, v23
	ds_bpermute_b32 v23, v16, v22
	s_waitcnt lgkmcnt(0)
	v_add_f32_e32 v22, v22, v23
	ds_bpermute_b32 v23, v17, v22
	s_and_saveexec_b64 s[24:25], s[2:3]
	s_cbranch_execz .LBB0_491
	s_waitcnt lgkmcnt(0)
	v_add_f32_e32 v22, v22, v23
	v_fmamk_f32 v22, v22, 0x3b000000, v18
	v_mul_f32_e32 v23, 0x4f800000, v22
	v_cmp_gt_f32_e32 vcc, s28, v22
	s_nop 1
	v_cndmask_b32_e32 v22, v22, v23, vcc
	v_sqrt_f32_e32 v23, v22
	s_nop 0
	v_add_u32_e32 v24, -1, v23
	v_fma_f32 v26, -v24, v23, v22
	v_add_u32_e32 v25, 1, v23
	v_cmp_ge_f32_e64 s[0:1], 0, v26
	s_nop 1
	v_cndmask_b32_e64 v24, v23, v24, s[0:1]
	v_fma_f32 v23, -v25, v23, v22
	v_cmp_lt_f32_e64 s[0:1], 0, v23
	s_nop 1
	v_cndmask_b32_e64 v23, v24, v25, s[0:1]
	v_mul_f32_e32 v24, 0x37800000, v23
	v_cndmask_b32_e32 v23, v23, v24, vcc
	v_cmp_class_f32_e32 vcc, v22, v19
	s_nop 1
	v_cndmask_b32_e32 v22, v23, v22, vcc
	v_div_scale_f32 v23, s[0:1], v22, v22, 1.0
	v_rcp_f32_e32 v24, v23
	s_add_u32 s0, s18, s10
	s_addc_u32 s1, s19, s11
	v_fma_f32 v25, -v23, v24, 1.0
	v_fmac_f32_e32 v24, v25, v24
	v_div_scale_f32 v25, vcc, 1.0, v22, 1.0
	v_mul_f32_e32 v26, v25, v24
	v_fma_f32 v27, -v23, v26, v25
	v_fmac_f32_e32 v26, v27, v24
	v_fma_f32 v23, -v23, v26, v25
	v_div_fmas_f32 v23, v23, v24, v26
	v_div_fixup_f32 v22, v23, v22, 1.0
	global_store_dword v20, v22, s[0:1]
.LBB0_491:
	s_or_b64 exec, exec, s[24:25]
	v_mov_b32_e32 v22, 0
	s_and_saveexec_b64 s[0:1], s[4:5]
	s_cbranch_execz .LBB0_493
	v_add_co_u32_e32 v22, vcc, 0x7c01000, v10
	s_waitcnt lgkmcnt(0)
	s_nop 0
	v_addc_co_u32_e32 v23, vcc, 0, v11, vcc
	s_waitcnt vmcnt(4)
	v_mov_b32_e32 v22, v40
	v_mov_b32_e32 v23, v41
	v_mov_b32_e32 v24, v42
	v_mov_b32_e32 v25, v43
	v_lshlrev_b32_e32 v26, 16, v22
	v_and_b32_e32 v27, 0xffff0000, v22
	v_and_b32_e32 v22, 0xffff0000, v23
	v_lshlrev_b32_e32 v23, 16, v23
	v_pk_mul_f32 v[26:27], v[26:27], v[26:27]
	v_pk_mul_f32 v[22:23], v[22:23], v[22:23]
	v_add_f32_e32 v26, v26, v27
	v_and_b32_e32 v28, 0xffff0000, v24
	v_lshlrev_b32_e32 v29, 16, v24
	v_add_f32_e32 v23, v23, v26
	v_pk_mul_f32 v[28:29], v[28:29], v[28:29]
	v_add_f32_e32 v22, v22, v23
	v_and_b32_e32 v24, 0xffff0000, v25
	v_lshlrev_b32_e32 v25, 16, v25
	v_add_f32_e32 v22, v29, v22
	v_pk_mul_f32 v[24:25], v[24:25], v[24:25]
	v_add_f32_e32 v22, v28, v22
	v_add_f32_e32 v22, v25, v22
	v_add_f32_e32 v22, v24, v22

; __device__ __forceinline__ unsigned pk2(float lo, float hi) { return f2bf(lo) | (f2bf(hi) << 16); }
; __global__ void __launch_bounds__(512, 2) fwd_kernel(Args a) {
;     ...
;             if (lane < 8) { const u32x4 v = *(const u32x4*)(pr + PC_KR + lane * 8); const int pos = m & (SEQ - 1), i0 = lane * 4;
;                 const f32x4 cs = *(const f32x4*)(cost + pos * 32 + i0), sn = *(const f32x4*)(sint + pos * 32 + i0);
;                 const f32x4 x1 = {bflo(v.x), bfhi(v.x), bflo(v.y), bfhi(v.y)}, x2 = {bflo(v.z), bfhi(v.z), bflo(v.w), bfhi(v.w)};
;                 const f32x4 o1 = x1 * cs - x2 * sn, o2 = x1 * sn + x2 * cs;
;                 u32x4 wv; wv.x = pk2(o1[0], o1[1]); wv.y = pk2(o1[2], o1[3]); wv.z = pk2(o2[0], o2[1]); wv.w = pk2(o2[2], o2[3]);
;                 *(u32x4*)(krope + (size_t)m * 64 + lane * 8) = wv; }
.LBB0_495:
	s_or_b64 exec, exec, s[24:25]
	s_and_saveexec_b64 s[0:1], s[6:7]
	s_cbranch_execz .LBB0_488
	v_add_co_u32_e32 v10, vcc, 0x7c01000, v10
	s_and_b32 s8, s15, 0x1ffe0
	s_nop 0
	v_addc_co_u32_e32 v11, vcc, 0, v11, vcc
	s_lshl_b32 s8, s8, 2
	s_waitcnt lgkmcnt(0)
	s_waitcnt vmcnt(2)
	v_mov_b32_e32 v22, v44
	v_mov_b32_e32 v23, v45
	v_mov_b32_e32 v24, v46
	v_mov_b32_e32 v25, v47
	v_mov_b32_e32 v26, v48
	v_mov_b32_e32 v27, v49
	v_mov_b32_e32 v28, v50
	v_mov_b32_e32 v29, v51
	v_mov_b32_e32 v30, v52
	v_mov_b32_e32 v31, v53
	v_mov_b32_e32 v32, v54
	v_mov_b32_e32 v33, v55
	v_lshl_add_u64 v[10:11], v[4:5], 0, s[8:9]
	v_lshl_add_u64 v[10:11], v[2:3], 0, s[8:9]
	v_lshlrev_b32_e32 v34, 16, v24
	v_and_b32_e32 v35, 0xffff0000, v24
	v_lshlrev_b32_e32 v24, 16, v25
	v_and_b32_e32 v25, 0xffff0000, v25
	v_lshlrev_b32_e32 v10, 16, v22
	v_and_b32_e32 v11, 0xffff0000, v22
	v_lshlrev_b32_e32 v22, 16, v23
	v_and_b32_e32 v23, 0xffff0000, v23
	v_pk_mul_f32 v[36:37], v[26:27], v[34:35]
	v_pk_mul_f32 v[38:39], v[28:29], v[24:25]
	v_pk_mul_f32 v[34:35], v[30:31], v[34:35]
	v_pk_mul_f32 v[24:25], v[32:33], v[24:25]
	v_pk_fma_f32 v[32:33], v[32:33], v[22:23], v[38:39] neg_lo:[0,0,1] neg_hi:[0,0,1]
	v_pk_fma_f32 v[30:31], v[30:31], v[10:11], v[36:37] neg_lo:[0,0,1] neg_hi:[0,0,1]
	v_pk_fma_f32 v[22:23], v[28:29], v[22:23], v[24:25]
	v_pk_fma_f32 v[10:11], v[26:27], v[10:11], v[34:35]
	v_bfe_u32 v24, v30, 16, 1
	v_bfe_u32 v26, v32, 16, 1
	v_bfe_u32 v28, v10, 16, 1
	v_bfe_u32 v34, v22, 16, 1
	v_bfe_u32 v25, v31, 16, 1
	v_bfe_u32 v27, v33, 16, 1
	v_bfe_u32 v29, v11, 16, 1
	v_bfe_u32 v35, v23, 16, 1
	v_add3_u32 v24, v30, v24, s29
	v_add3_u32 v26, v32, v26, s29
	v_add3_u32 v10, v10, v28, s29
	v_add3_u32 v22, v22, v34, s29
	v_add3_u32 v25, v31, v25, s29
	v_add3_u32 v27, v33, v27, s29
	v_add3_u32 v11, v11, v29, s29
	v_add3_u32 v28, v23, v35, s29
	v_lshrrev_b32_e32 v23, 16, v24
	v_lshrrev_b32_e32 v24, 16, v26
	v_lshrrev_b32_e32 v10, 16, v10
	v_lshrrev_b32_e32 v26, 16, v22
	v_and_or_b32 v22, v25, s27, v23
	v_and_or_b32 v23, v27, s27, v24
	v_and_or_b32 v24, v11, s27, v10
	v_and_or_b32 v25, v28, s27, v26
	v_lshl_add_u64 v[10:11], s[18:19], 0, v[6:7]
	global_store_dwordx4 v[10:11], v[22:25], off
	s_branch .LBB0_488
